# c29: SSD pass-1 staging reassigned and straight-line like pass 3; the C rows and raw x rows pass 1 never reads are no longer loaded or staged
# speedup vs baseline: 1.0351x; 1.0111x over previous
; template <int PASS>
; __device__ void ssd_item(const Params& p, int item, int l, unsigned char* smem) {
;     ...
;     float segtot = 0.f;
;     const size_t tokb = (size_t)b * SEQ;
;     const unsigned char* xb_ = (const unsigned char*)((const bf16_t*)(p.ws + WS_XBCC) + tokb * 1024);
;     unsigned soff[5];
; #pragma unroll
;     for (int i = 0; i < 5; ++i) { const int u = tid + 256 * i, lrow = u / 40, ci = u % 40;
;         const int scol = ci < 8 ? h * 64 + ci * 8 : (ci < 24 ? 512 + grp * 128 + (ci * 8 - 64) : 768 + grp * 128 + (ci * 8 - 192));
;         soff[i] = (unsigned)((lrow * 1024 + scol) * 2); }
;     for (int si = 0; si < NSUB; ++si) {
;         const int scn = dir ? (NSUB - 1 - si) : si;
;         const int t0 = seg * SEGLEN + scn * TSUB;
;         __syncthreads();
;         u32x4 raw[5];
; #pragma unroll
;         for (int i = 0; i < 5; ++i) raw[i] = *(const u32x4*)(xb_ + ((unsigned)(t0 * 2048) + soff[i]));
.LBB0_733:
	s_andn2_saveexec_b64 s[46:47], s[50:51]
	v_add_u32_e32 v10, s22, v9
	s_or_b64 exec, exec, s[46:47]
	v_lshlrev_b32_e32 v11, 11, v57
	v_lshl_add_u32 v60, v7, 1, v11
	v_lshlrev_b32_e32 v7, 11, v56
	v_lshl_add_u32 v61, v5, 1, v7
	v_lshlrev_b32_e32 v5, 11, v55
	v_lshl_add_u32 v62, v3, 1, v5
	v_lshlrev_b32_e32 v3, 11, v53
	v_lshl_add_u32 v63, v2, 1, v3
	v_lshlrev_b32_e32 v2, 11, v58
	v_lshl_add_u32 v64, v10, 1, v2
	v_lshrrev_b32_e32 v2, 1, v52
	v_bfe_u32 v3, v52, 2, 2
	v_ashrrev_i32_e32 v59, 6, v52
	v_and_or_b32 v2, v2, 24, v3
	v_mul_u32_u24_e32 v3, 0x90, v2
	v_lshlrev_b32_e32 v7, 5, v59
	v_add3_u32 v3, v54, v3, v7
	v_cmp_lt_u32_e64 s[46:47], 23, v1
	v_mul_lo_u32 v7, v53, s0
	v_lshlrev_b32_e32 v1, 4, v1
	v_add3_u32 v66, v54, v7, v1
	v_mul_lo_u32 v7, v53, s3
	s_lshl_b64 s[22:23], s[48:49], 24
	v_add3_u32 v68, v54, v7, v1
	v_cmp_lt_u32_e64 s[48:49], 23, v0
	v_mul_lo_u32 v1, v55, s0
	v_lshlrev_b32_e32 v0, 4, v0
	v_add3_u32 v69, v54, v1, v0
	v_mul_lo_u32 v1, v55, s3
	v_add3_u32 v71, v54, v1, v0
	v_mul_lo_u32 v0, v56, s0
	v_lshlrev_b32_e32 v1, 4, v4
	v_add3_u32 v72, v54, v0, v1
	v_mul_lo_u32 v0, v56, s3
	v_add3_u32 v74, v54, v0, v1
	v_mul_lo_u32 v0, v57, s0
	v_lshlrev_b32_e32 v1, 4, v6
	v_add3_u32 v75, v54, v0, v1
	v_mul_lo_u32 v0, v57, s3
	v_lshlrev_b32_e32 v5, 3, v52
	v_add3_u32 v77, v54, v0, v1
	v_mul_lo_u32 v0, v58, s0
	v_lshlrev_b32_e32 v1, 1, v9
	s_add_u32 s64, s18, s22
	v_and_b32_e32 v5, 24, v5
	v_mad_u32_u24 v2, v2, s0, v54
	v_add3_u32 v78, v54, v0, v1
	v_mul_lo_u32 v0, v58, s3
	v_mov_b32_e32 v65, 0
	s_addc_u32 s65, s19, s23
	s_lshl_b32 s12, s12, 20
	v_add_u32_e32 v67, 0xffffff80, v66
	v_add_u32_e32 v70, 0xffffff80, v69
	v_cmp_lt_u32_e64 s[50:51], 23, v4
	v_add_u32_e32 v73, 0xffffff80, v72
	v_cmp_lt_u32_e64 s[52:53], 23, v6
	v_add_u32_e32 v76, 0xffffff80, v75
	v_cmp_lt_u32_e64 s[54:55], 23, v8
	v_add_u32_e32 v79, 0xffffff80, v78
	v_add3_u32 v80, v54, v0, v1
	s_mov_b32 s22, 0
	s_mov_b32 s23, 15
	v_add_u32_e32 v82, v3, v5
	v_add_u32_e32 v83, v2, v5
	v_mov_b32_e32 v0, 0
	v_mov_b32_e32 v1, v65
	v_mov_b32_e32 v2, v65
	v_mov_b32_e32 v3, v65
	v_mov_b32_e32 v4, 0
	v_mov_b32_e32 v5, v65
	v_mov_b32_e32 v6, v65
	v_mov_b32_e32 v7, v65
	v_mov_b32_e32 v8, 0
	v_mov_b32_e32 v9, v65
	v_mov_b32_e32 v10, v65
	v_mov_b32_e32 v11, v65
	v_mov_b32_e32 v16, 0
	v_mov_b32_e32 v17, v65
	v_mov_b32_e32 v18, v65
	v_mov_b32_e32 v19, v65
	v_mov_b32_e32 v12, 0
	v_mov_b32_e32 v13, v65
	v_mov_b32_e32 v14, v65
	v_mov_b32_e32 v15, v65
	v_mov_b32_e32 v20, 0
	v_mov_b32_e32 v21, v65
	v_mov_b32_e32 v22, v65
	v_mov_b32_e32 v23, v65
	v_mov_b32_e32 v24, 0
	v_mov_b32_e32 v25, v65
	v_mov_b32_e32 v26, v65
	v_mov_b32_e32 v27, v65
	v_mov_b32_e32 v28, 0
	v_mov_b32_e32 v29, v65
	v_mov_b32_e32 v30, v65
	v_mov_b32_e32 v31, v65
	s_and_b64 s[24:25], vcc, exec
	s_cselect_b32 s99, 0, 15
	s_cselect_b32 s100, 1, 14
	s_lshl_b32 s99, s99, 16
	s_add_i32 s99, s99, s12
	s_lshl_b32 s100, s100, 16
	s_add_i32 s100, s100, s12
	s_bfe_u32 s88, s62, 0x30004
	s_lshr_b32 s89, s88, 2
	s_lshl_b32 s88, s88, 7
	s_lshl_b32 s89, s89, 8
	s_addk_i32 s89, 0x400
	v_and_b32_e32 v146, 0xff, v210
	v_lshrrev_b32_e32 v53, 3, v146
	v_and_b32_e32 v147, 7, v146
	v_lshlrev_b32_e32 v63, 11, v53
	v_lshl_add_u32 v63, v147, 4, v63
	v_add_u32_e32 v63, s88, v63
	v_mul_u32_u24_e32 v209, 0x90, v53
	v_lshl_add_u32 v209, v147, 4, v209
	v_add_u32_e32 v209, v54, v209
	v_lshrrev_b32_e32 v147, 4, v146
	v_and_b32_e32 v146, 15, v146
	v_lshlrev_b32_e32 v62, 11, v147
	v_lshl_add_u32 v62, v146, 4, v62
	v_add_u32_e32 v62, s89, v62
	v_add_u32_e32 v61, 0x8000, v62
	v_mul_u32_u24_e32 v208, 0x110, v147
	v_lshl_add_u32 v208, v146, 4, v208
	v_add_u32_e32 v208, v54, v208
	v_add_u32_e32 v146, s99, v63
	global_load_dwordx4 v[104:107], v146, s[64:65]
	v_add_u32_e32 v147, s99, v62
	global_load_dwordx4 v[108:111], v147, s[64:65]
	v_add_u32_e32 v146, s99, v61
	global_load_dwordx4 v[112:115], v146, s[64:65]
	v_add_u32_e32 v146, s100, v63
	global_load_dwordx4 v[124:127], v146, s[64:65]
	v_add_u32_e32 v147, s100, v62
	global_load_dwordx4 v[128:131], v147, s[64:65]
	v_add_u32_e32 v146, s100, v61
	global_load_dwordx4 v[132:135], v146, s[64:65]
	s_branch .LBB0_737

; template <int PASS>
; __device__ void ssd_item(const Params& p, int item, int l, unsigned char* smem) {
;     ...
;     for (int si = 0; si < NSUB; ++si) {
;         const int scn = dir ? (NSUB - 1 - si) : si;
;         const int t0 = seg * SEGLEN + scn * TSUB;
;         __syncthreads();
;         u32x4 raw[5];
; #pragma unroll
;         for (int i = 0; i < 5; ++i) raw[i] = *(const u32x4*)(xb_ + ((unsigned)(t0 * 2048) + soff[i]));
.LBB0_737:
	s_add_i32 s99, s22, 2
	s_sub_i32 s100, 15, s99
	s_and_b64 s[24:25], vcc, exec
	s_cselect_b32 s101, s99, s100
	s_cselect_b32 s24, s22, s23
	s_lshl_b32 s101, s101, 16
	s_add_i32 s101, s101, s12
	s_waitcnt lgkmcnt(0)
	s_barrier
	s_cmp_gt_u32 s22, 13
	s_cbranch_scc1 .Lssd1_tailwait
	s_waitcnt vmcnt(3)
	s_branch .Lssd1_w

; __device__ __forceinline__ unsigned pk2(float lo, float hi) { f32x2 v = {lo, hi}; bf16x2_t b = __builtin_convertvector(v, bf16x2_t); return __builtin_bit_cast(unsigned, b); }
; __device__ __forceinline__ float bflo(unsigned u) { return __uint_as_float(u << 16); }
; __device__ __forceinline__ float bfhi(unsigned u) { return __uint_as_float(u & 0xffff0000u); }
; template <int PASS>
; __device__ void ssd_item(const Params& p, int item, int l, unsigned char* smem) {
;     ...
;         for (int i = 0; i < 5; ++i) raw[i] = *(const u32x4*)(xb_ + ((unsigned)(t0 * 2048) + soff[i]));
;         const float* s_dt = s_dta + scn * TSUB; const float* s_c = s_cA + scn * TSUB; const float* s_rs = s_rsA + scn * TSUB; const float* s_wl = s_wlA + scn * TSUB;
;         const float stot = s_totA[scn];
;         segtot += stot;
; #pragma unroll
;         for (int i = 0; i < 5; ++i) { const int u = tid + 256 * i, lrow = u / 40, ci = u % 40, lc = ci * 8; const u32x4 o = raw[i];
;             if (ci < 8) { *(u32x4*)(Xs + lrow * 72 + lc) = o; const float wl = s_wl[lrow];
;                 u32x4 o2; o2.x = pk2(bflo(o.x) * wl, bfhi(o.x) * wl); o2.y = pk2(bflo(o.y) * wl, bfhi(o.y) * wl); o2.z = pk2(bflo(o.z) * wl, bfhi(o.z) * wl); o2.w = pk2(bflo(o.w) * wl, bfhi(o.w) * wl);
;                 *(u32x4*)(Xws + lrow * 72 + lc) = o2; }
;             else if (ci < 24) *(u32x4*)(Bs + lrow * 136 + (lc - 64)) = o;
;             else *(u32x4*)(Cs + lrow * 136 + (lc - 192)) = o; }
.Lssd1_w:
	s_bitcmp1_b32 s22, 0
	s_cbranch_scc1 .Lssd1_odd
	v_mov_b32_e32 v48, v104
	v_mov_b32_e32 v49, v105
	v_mov_b32_e32 v50, v106
	v_mov_b32_e32 v51, v107
	v_mov_b32_e32 v44, v108
	v_mov_b32_e32 v45, v109
	v_mov_b32_e32 v46, v110
	v_mov_b32_e32 v47, v111
	v_mov_b32_e32 v40, v112
	v_mov_b32_e32 v41, v113
	v_mov_b32_e32 v42, v114
	v_mov_b32_e32 v43, v115
	s_cmp_gt_u32 s22, 13
	s_cbranch_scc1 .Lssd1_join
	v_add_u32_e32 v146, s101, v63
	global_load_dwordx4 v[104:107], v146, s[64:65]
	v_add_u32_e32 v147, s101, v62
	global_load_dwordx4 v[108:111], v147, s[64:65]
	v_add_u32_e32 v146, s101, v61
	global_load_dwordx4 v[112:115], v146, s[64:65]
	s_branch .Lssd1_join
.Lssd1_odd:
	v_mov_b32_e32 v48, v124
	v_mov_b32_e32 v49, v125
	v_mov_b32_e32 v50, v126
	v_mov_b32_e32 v51, v127
	v_mov_b32_e32 v44, v128
	v_mov_b32_e32 v45, v129
	v_mov_b32_e32 v46, v130
	v_mov_b32_e32 v47, v131
	v_mov_b32_e32 v40, v132
	v_mov_b32_e32 v41, v133
	v_mov_b32_e32 v42, v134
	v_mov_b32_e32 v43, v135
	s_cmp_gt_u32 s22, 13
	s_cbranch_scc1 .Lssd1_join
	v_add_u32_e32 v146, s101, v63
	global_load_dwordx4 v[124:127], v146, s[64:65]
	v_add_u32_e32 v147, s101, v62
	global_load_dwordx4 v[128:131], v147, s[64:65]
	v_add_u32_e32 v146, s101, v61
	global_load_dwordx4 v[132:135], v146, s[64:65]
.Lssd1_join:
	v_lshl_add_u32 v85, s24, 7, v54
	s_mulk_i32 s24, 0xff84
	v_add_u32_e32 v84, s24, v85
	ds_read_b32 v84, v84 offset:54272
	v_lshl_add_u32 v150, v53, 2, v85
	ds_read_b32 v150, v150 offset:50688
	ds_write_b128 v208, v[44:47]
	ds_write_b128 v208, v[40:43] offset:4352
	s_waitcnt lgkmcnt(2)
	v_lshlrev_b32_e32 v88, 16, v48
	v_and_b32_e32 v89, 0xffff0000, v48
	v_pk_mul_f32 v[88:89], v[150:151], v[88:89] op_sel_hi:[0,1]
	v_cvt_pk_bf16_f32 v48, v88, v89
	v_lshlrev_b32_e32 v88, 16, v49
	v_and_b32_e32 v89, 0xffff0000, v49
	v_pk_mul_f32 v[88:89], v[150:151], v[88:89] op_sel_hi:[0,1]
	v_cvt_pk_bf16_f32 v49, v88, v89
	v_lshlrev_b32_e32 v88, 16, v50
	v_and_b32_e32 v89, 0xffff0000, v50
	v_pk_mul_f32 v[88:89], v[150:151], v[88:89] op_sel_hi:[0,1]
	v_cvt_pk_bf16_f32 v50, v88, v89
	v_lshlrev_b32_e32 v88, 16, v51
	v_and_b32_e32 v89, 0xffff0000, v51
	v_pk_mul_f32 v[88:89], v[150:151], v[88:89] op_sel_hi:[0,1]
	v_cvt_pk_bf16_f32 v51, v88, v89
	ds_write_b128 v209, v[48:51] offset:22016
	s_branch .LBB0_736
